# conv values read with ds_read_u16_d16_hi (land as bf16<<16 directly), 16 shifts fewer per gate segment
# speedup vs baseline: 1.0027x; 1.0027x over previous
; #define LAS __attribute__((address_space(3)))
; template <int dir>
; __device__ __forceinline__ void lru_pass(LAS unsigned char* lds, const Params& P, int b, int h, int q, bool dry) {
;     ...
;             const int sbase = 32 * wid + 16 * g;
;             { const int sl = 32 * wid + s_i; const int tlA = dir == 0 ? sl : 255 - sl;
;               const LAS unsigned char* ap = XC + tlA * XC_PITCH + 16 * g;
;               const LAS unsigned char* wrp = WB + nl * XC_PITCH + 16 * g; const LAS unsigned char* wip = wrp + 32 * XC_PITCH;
; #pragma unroll
;               for (int ks = 0; ks < 8; ++ks) { const bf16x8 A = *(const LAS bf16x8*)(ap + 32 * ks);
;                   const bf16x8 Br = *(const LAS bf16x8*)(wrp + 32 * ks), Bi = *(const LAS bf16x8*)(wip + 32 * ks);
;                   zr = __builtin_amdgcn_mfma_f32_32x32x16_bf16(A, Br, zr, 0, 0, 0); zi = __builtin_amdgcn_mfma_f32_32x32x16_bf16(A, Bi, zi, 0, 0, 0); } }
;             unsigned xcb[16], pk[16];
; #pragma unroll
;             for (int v = 0; v < 16; ++v) { const int s = sbase + v; const int tl = dir == 0 ? s : 255 - s; xcb[v] = *(const LAS bf16_t*)(XC + tl * XC_PITCH + chl * 2);
;                 if (dir == 0) pk[v] = *(const LAS bf16_t*)(TIN + tl * IO_NP + nl * 2); else pk[v] = *(const LAS unsigned*)(TIN + tl * IO_WP + nl * 4); }
;             float Pp = 1.f, E = 0.f;
; #pragma unroll
;             for (int v = 0; v < 16; ++v) {
;                 const float xcv = __uint_as_float(xcb[v] << 16);
;                 const float r = __builtin_amdgcn_rcpf(1.0f + __builtin_amdgcn_exp2f(zr[v]));
;                 const float ig = __builtin_amdgcn_rcpf(1.0f + __builtin_amdgcn_exp2f(zi[v]));
;                 const float a = __builtin_amdgcn_exp2f(cl * r);
;                 const float sq = __builtin_amdgcn_sqrtf(fmaf(-a, a, 1.0f));
.Llruf_wres:
	ds_read_b128 v[120:123], v160
	ds_read_b128 v[124:127], v160 offset:32
	ds_read_b128 v[168:171], v160 offset:64
	ds_read_b128 v[172:175], v160 offset:96
	ds_read_b128 v[176:179], v160 offset:128
	ds_read_b128 v[180:183], v160 offset:160
	ds_read_b128 v[184:187], v160 offset:192
	ds_read_b128 v[188:191], v160 offset:224
	ds_read_b128 v[236:239], v161 offset:8704
	ds_read_b128 v[240:243], v161 offset:8736
	ds_read_b128 v[244:247], v161 offset:8768
	ds_read_b128 v[248:251], v161 offset:8800
	s_waitcnt lgkmcnt(11)
	v_mfma_f32_32x32x16_bf16 v[32:47], v[120:123], v[204:207], v[0:15]
	s_waitcnt lgkmcnt(10)
	v_mfma_f32_32x32x16_bf16 v[32:47], v[124:127], v[208:211], v[32:47]
	s_waitcnt lgkmcnt(9)
	v_mfma_f32_32x32x16_bf16 v[32:47], v[168:171], v[212:215], v[32:47]
	s_waitcnt lgkmcnt(8)
	v_mfma_f32_32x32x16_bf16 v[32:47], v[172:175], v[216:219], v[32:47]
	s_waitcnt lgkmcnt(7)
	v_mfma_f32_32x32x16_bf16 v[32:47], v[176:179], v[220:223], v[32:47]
	s_waitcnt lgkmcnt(6)
	v_mfma_f32_32x32x16_bf16 v[32:47], v[180:183], v[224:227], v[32:47]
	s_waitcnt lgkmcnt(5)
	v_mfma_f32_32x32x16_bf16 v[32:47], v[184:187], v[228:231], v[32:47]
	s_waitcnt lgkmcnt(4)
	v_mfma_f32_32x32x16_bf16 v[32:47], v[188:191], v[232:235], v[32:47]
	s_waitcnt lgkmcnt(3)
	v_mfma_f32_32x32x16_bf16 v[48:63], v[120:123], v[236:239], v[16:31]
	ds_read_b128 v[236:239], v161 offset:8832
	s_nop 9
	v_exp_f32_e32 v32, v32
	v_exp_f32_e32 v33, v33
	v_exp_f32_e32 v34, v34
	v_exp_f32_e32 v35, v35
	v_exp_f32_e32 v36, v36
	v_exp_f32_e32 v37, v37
	v_exp_f32_e32 v38, v38
	v_exp_f32_e32 v39, v39
	s_waitcnt lgkmcnt(3)
	v_mfma_f32_32x32x16_bf16 v[48:63], v[124:127], v[240:243], v[48:63]
	ds_read_b128 v[240:243], v161 offset:8864
	v_exp_f32_e32 v40, v40
	v_exp_f32_e32 v41, v41
	v_exp_f32_e32 v42, v42
	v_exp_f32_e32 v43, v43
	v_exp_f32_e32 v44, v44
	v_exp_f32_e32 v45, v45
	v_exp_f32_e32 v46, v46
	v_exp_f32_e32 v47, v47
	s_waitcnt lgkmcnt(3)
	v_mfma_f32_32x32x16_bf16 v[48:63], v[168:171], v[244:247], v[48:63]
	ds_read_b128 v[244:247], v161 offset:8896
	v_fma_f32 v32, v32, v138, v138
	v_fma_f32 v33, v33, v138, v138
	v_fma_f32 v34, v34, v138, v138
	v_fma_f32 v35, v35, v138, v138
	v_fma_f32 v36, v36, v138, v138
	v_fma_f32 v37, v37, v138, v138
	v_fma_f32 v38, v38, v138, v138
	v_fma_f32 v39, v39, v138, v138
	s_waitcnt lgkmcnt(3)
	v_mfma_f32_32x32x16_bf16 v[48:63], v[172:175], v[248:251], v[48:63]
	ds_read_b128 v[248:251], v161 offset:8928
	v_fma_f32 v40, v40, v138, v138
	v_fma_f32 v41, v41, v138, v138
	v_fma_f32 v42, v42, v138, v138
	v_fma_f32 v43, v43, v138, v138
	v_fma_f32 v44, v44, v138, v138
	v_fma_f32 v45, v45, v138, v138
	v_fma_f32 v46, v46, v138, v138
	v_fma_f32 v47, v47, v138, v138
	s_waitcnt lgkmcnt(3)
	v_mfma_f32_32x32x16_bf16 v[48:63], v[176:179], v[236:239], v[48:63]
	v_rcp_f32_e32 v32, v32
	v_rcp_f32_e32 v33, v33
	v_rcp_f32_e32 v34, v34
	v_rcp_f32_e32 v35, v35
	v_rcp_f32_e32 v36, v36
	v_rcp_f32_e32 v37, v37
	v_rcp_f32_e32 v38, v38
	v_rcp_f32_e32 v39, v39
	s_waitcnt lgkmcnt(2)
	v_mfma_f32_32x32x16_bf16 v[48:63], v[180:183], v[240:243], v[48:63]
	v_rcp_f32_e32 v40, v40
	v_rcp_f32_e32 v41, v41
	v_rcp_f32_e32 v42, v42
	v_rcp_f32_e32 v43, v43
	v_rcp_f32_e32 v44, v44
	v_rcp_f32_e32 v45, v45
	v_rcp_f32_e32 v46, v46
	v_rcp_f32_e32 v47, v47
	s_waitcnt lgkmcnt(1)
	v_mfma_f32_32x32x16_bf16 v[48:63], v[184:187], v[244:247], v[48:63]
	v_exp_f32_e32 v32, v32
	v_exp_f32_e32 v33, v33
	v_exp_f32_e32 v34, v34
	v_exp_f32_e32 v35, v35
	v_exp_f32_e32 v36, v36
	v_exp_f32_e32 v37, v37
	v_exp_f32_e32 v38, v38
	v_exp_f32_e32 v39, v39
	s_waitcnt lgkmcnt(0)
; #define LAS __attribute__((address_space(3)))
; template <int dir>
; __device__ __forceinline__ void lru_pass(LAS unsigned char* lds, const Params& P, int b, int h, int q, bool dry) {
;     ...
;             for (int v = 0; v < 16; ++v) { const int s = sbase + v; const int tl = dir == 0 ? s : 255 - s; xcb[v] = *(const LAS bf16_t*)(XC + tl * XC_PITCH + chl * 2);
;                 if (dir == 0) pk[v] = *(const LAS bf16_t*)(TIN + tl * IO_NP + nl * 2); else pk[v] = *(const LAS unsigned*)(TIN + tl * IO_WP + nl * 4); }
;             float Pp = 1.f, E = 0.f;
; #pragma unroll
;             for (int v = 0; v < 16; ++v) {
;                 const float xcv = __uint_as_float(xcb[v] << 16);
;                 const float r = __builtin_amdgcn_rcpf(1.0f + __builtin_amdgcn_exp2f(zr[v]));
;                 const float ig = __builtin_amdgcn_rcpf(1.0f + __builtin_amdgcn_exp2f(zi[v]));
;                 const float a = __builtin_amdgcn_exp2f(cl * r);
;                 const float sq = __builtin_amdgcn_sqrtf(fmaf(-a, a, 1.0f));
;                 const float u = sq * ig * xcv;
;                 E = fmaf(a, E, u); Pp *= a; zr[v] = E; zi[v] = Pp; }
;             const float Po = __shfl_xor(Pp, 32), Eo = __shfl_xor(E, 32);
;             const float P0 = g ? Po : Pp, E0 = g ? Eo : E, P1 = g ? Pp : Po, E1 = g ? E : Eo;
;             if (g == 0) { AGG[(wid * 2 + 0) * 32 + nl] = P0 * P1; AGG[(wid * 2 + 1) * 32 + nl] = fmaf(P1, E0, E1); }
	v_mfma_f32_32x32x16_bf16 v[48:63], v[188:191], v[248:251], v[48:63]
	v_exp_f32_e32 v40, v40
	v_exp_f32_e32 v41, v41
	v_exp_f32_e32 v42, v42
	v_exp_f32_e32 v43, v43
	v_exp_f32_e32 v44, v44
	v_exp_f32_e32 v45, v45
	v_exp_f32_e32 v46, v46
	v_exp_f32_e32 v47, v47
	ds_read_u16_d16_hi v152, v162
	ds_read_u16_d16_hi v154, v162 offset:272
	ds_read_u16_d16_hi v155, v162 offset:544
	ds_read_u16_d16_hi v157, v162 offset:816
	ds_read_u16_d16_hi v196, v162 offset:1088
	ds_read_u16_d16_hi v197, v162 offset:1360
	ds_read_u16_d16_hi v177, v162 offset:1632
	ds_read_u16_d16_hi v178, v162 offset:1904
	ds_read_u16_d16_hi v179, v162 offset:2176
	ds_read_u16_d16_hi v180, v162 offset:2448
	ds_read_u16_d16_hi v181, v162 offset:2720
	ds_read_u16_d16_hi v182, v162 offset:2992
	ds_read_u16_d16_hi v183, v162 offset:3264
	ds_read_u16_d16_hi v184, v162 offset:3536
	ds_read_u16_d16_hi v185, v162 offset:3808
	ds_read_u16_d16_hi v187, v162 offset:4080
	v_exp_f32_e32 v48, v48
	v_exp_f32_e32 v49, v49
	v_exp_f32_e32 v50, v50
	v_exp_f32_e32 v51, v51
	v_exp_f32_e32 v52, v52
	v_exp_f32_e32 v53, v53
	v_exp_f32_e32 v54, v54
	v_exp_f32_e32 v55, v55
	v_exp_f32_e32 v56, v56
	v_exp_f32_e32 v57, v57
	v_exp_f32_e32 v58, v58
	v_exp_f32_e32 v59, v59
	v_exp_f32_e32 v60, v60
	v_exp_f32_e32 v61, v61
	v_exp_f32_e32 v62, v62
	v_exp_f32_e32 v63, v63
	v_pk_add_f32 v[48:49], v[48:49], 1.0 op_sel_hi:[1,0]
	v_pk_add_f32 v[50:51], v[50:51], 1.0 op_sel_hi:[1,0]
	v_pk_add_f32 v[52:53], v[52:53], 1.0 op_sel_hi:[1,0]
	v_pk_add_f32 v[54:55], v[54:55], 1.0 op_sel_hi:[1,0]
	v_pk_add_f32 v[56:57], v[56:57], 1.0 op_sel_hi:[1,0]
	v_pk_add_f32 v[58:59], v[58:59], 1.0 op_sel_hi:[1,0]
	v_pk_add_f32 v[60:61], v[60:61], 1.0 op_sel_hi:[1,0]
	v_pk_add_f32 v[62:63], v[62:63], 1.0 op_sel_hi:[1,0]
	v_rcp_f32_e32 v48, v48
	v_rcp_f32_e32 v49, v49
	v_rcp_f32_e32 v50, v50
	v_rcp_f32_e32 v51, v51
	v_rcp_f32_e32 v52, v52
	v_rcp_f32_e32 v53, v53
	v_rcp_f32_e32 v54, v54
	v_rcp_f32_e32 v55, v55
	v_rcp_f32_e32 v56, v56
	v_rcp_f32_e32 v57, v57
	v_rcp_f32_e32 v58, v58
	v_rcp_f32_e32 v59, v59
	v_rcp_f32_e32 v60, v60
	v_rcp_f32_e32 v61, v61
	v_rcp_f32_e32 v62, v62
	v_rcp_f32_e32 v63, v63
	s_waitcnt lgkmcnt(0)
	v_pk_fma_f32 v[120:121], v[32:33], v[32:33], 1.0 op_sel_hi:[1,1,0] neg_lo:[1,0,0] neg_hi:[1,0,0]
	v_pk_fma_f32 v[122:123], v[34:35], v[34:35], 1.0 op_sel_hi:[1,1,0] neg_lo:[1,0,0] neg_hi:[1,0,0]
	v_sqrt_f32_e32 v120, v120
	v_sqrt_f32_e32 v121, v121
	v_sqrt_f32_e32 v122, v122
	v_sqrt_f32_e32 v123, v123
	v_pk_mul_f32 v[120:121], v[120:121], v[48:49]
	v_pk_mul_f32 v[122:123], v[122:123], v[50:51]
	v_mul_f32_e32 v49, v120, v152
	v_mul_f32_e32 v172, v121, v154
	v_mul_f32_e32 v173, v122, v155
	v_mul_f32_e32 v174, v123, v157
	v_pk_fma_f32 v[120:121], v[36:37], v[36:37], 1.0 op_sel_hi:[1,1,0] neg_lo:[1,0,0] neg_hi:[1,0,0]
	v_pk_fma_f32 v[122:123], v[38:39], v[38:39], 1.0 op_sel_hi:[1,1,0] neg_lo:[1,0,0] neg_hi:[1,0,0]
	v_sqrt_f32_e32 v120, v120
	v_sqrt_f32_e32 v121, v121
	v_sqrt_f32_e32 v122, v122
	v_sqrt_f32_e32 v123, v123
	v_pk_mul_f32 v[120:121], v[120:121], v[52:53]
	v_pk_mul_f32 v[122:123], v[122:123], v[54:55]
	v_mul_f32_e32 v175, v120, v196
	v_mul_f32_e32 v176, v121, v197
	v_mul_f32_e32 v177, v122, v177
	v_mul_f32_e32 v178, v123, v178
	v_pk_fma_f32 v[120:121], v[40:41], v[40:41], 1.0 op_sel_hi:[1,1,0] neg_lo:[1,0,0] neg_hi:[1,0,0]
	v_pk_fma_f32 v[122:123], v[42:43], v[42:43], 1.0 op_sel_hi:[1,1,0] neg_lo:[1,0,0] neg_hi:[1,0,0]
	v_sqrt_f32_e32 v120, v120
	v_sqrt_f32_e32 v121, v121
	v_sqrt_f32_e32 v122, v122
	v_sqrt_f32_e32 v123, v123
	v_pk_mul_f32 v[120:121], v[120:121], v[56:57]
	v_pk_mul_f32 v[122:123], v[122:123], v[58:59]
	v_mul_f32_e32 v179, v120, v179
	v_mul_f32_e32 v180, v121, v180
	v_mul_f32_e32 v181, v122, v181
	v_mul_f32_e32 v182, v123, v182
	v_pk_fma_f32 v[120:121], v[44:45], v[44:45], 1.0 op_sel_hi:[1,1,0] neg_lo:[1,0,0] neg_hi:[1,0,0]
	v_pk_fma_f32 v[122:123], v[46:47], v[46:47], 1.0 op_sel_hi:[1,1,0] neg_lo:[1,0,0] neg_hi:[1,0,0]
	v_sqrt_f32_e32 v120, v120
	v_sqrt_f32_e32 v121, v121
	v_sqrt_f32_e32 v122, v122
	v_sqrt_f32_e32 v123, v123
	v_pk_mul_f32 v[120:121], v[120:121], v[60:61]
	v_pk_mul_f32 v[122:123], v[122:123], v[62:63]
	v_mul_f32_e32 v183, v120, v183
	v_mul_f32_e32 v184, v121, v184
	v_mul_f32_e32 v63, v122, v185
	v_mul_f32_e32 v185, v123, v187
	v_mov_b32_e32 v171, v32
	v_fmac_f32_e32 v49, 0, v32
	v_fmac_f32_e32 v172, v33, v49
	v_mul_f32_e32 v50, v171, v33
	v_fmac_f32_e32 v173, v34, v172
	v_mul_f32_e32 v51, v50, v34
	v_fmac_f32_e32 v174, v35, v173
	v_mul_f32_e32 v52, v51, v35
	v_fmac_f32_e32 v175, v36, v174
	v_mul_f32_e32 v53, v52, v36
	v_fmac_f32_e32 v176, v37, v175
	v_mul_f32_e32 v54, v53, v37
	v_fmac_f32_e32 v177, v38, v176
	v_mul_f32_e32 v55, v54, v38
	v_fmac_f32_e32 v178, v39, v177
	v_mul_f32_e32 v56, v55, v39
	v_fmac_f32_e32 v179, v40, v178
	v_mul_f32_e32 v57, v56, v40
	v_fmac_f32_e32 v180, v41, v179
	v_mul_f32_e32 v58, v57, v41
	v_fmac_f32_e32 v181, v42, v180
	v_mul_f32_e32 v59, v58, v42
	v_fmac_f32_e32 v182, v43, v181
	v_mul_f32_e32 v60, v59, v43
	v_fmac_f32_e32 v183, v44, v182
	v_mul_f32_e32 v61, v60, v44
	v_fmac_f32_e32 v184, v45, v183
	v_mul_f32_e32 v62, v61, v45
	v_fmac_f32_e32 v63, v46, v184
	v_mul_f32_e32 v186, v62, v46
	v_fmac_f32_e32 v185, v47, v63
	v_mul_f32_e32 v187, v186, v47
	v_mov_b32_e32 v188, v187
	v_mov_b32_e32 v252, v187
	v_mov_b32_e32 v189, v185
	v_mov_b32_e32 v253, v185
	s_nop 1
	v_permlane32_swap_b32 v188, v252
	v_permlane32_swap_b32 v189, v253
	s_and_saveexec_b64 s[18:19], vcc
	s_cbranch_execz .LBB0_299
	v_fma_f32 v32, v252, v189, v253
	v_mul_f32_e32 v33, v188, v252
	v_add_u32_e32 v35, s98, v147
	ds_write2_b32 v35, v33, v32 offset1:32

; #define LAS __attribute__((address_space(3)))
; template <int dir>
; __device__ __forceinline__ void lru_pass(LAS unsigned char* lds, const Params& P, int b, int h, int q, bool dry) {
;     ...
;             const int sbase = 32 * wid + 16 * g;
;             { const int sl = 32 * wid + s_i; const int tlA = dir == 0 ? sl : 255 - sl;
;               const LAS unsigned char* ap = XC + tlA * XC_PITCH + 16 * g;
;               const LAS unsigned char* wrp = WB + nl * XC_PITCH + 16 * g; const LAS unsigned char* wip = wrp + 32 * XC_PITCH;
; #pragma unroll
;               for (int ks = 0; ks < 8; ++ks) { const bf16x8 A = *(const LAS bf16x8*)(ap + 32 * ks);
;                   const bf16x8 Br = *(const LAS bf16x8*)(wrp + 32 * ks), Bi = *(const LAS bf16x8*)(wip + 32 * ks);
;                   zr = __builtin_amdgcn_mfma_f32_32x32x16_bf16(A, Br, zr, 0, 0, 0); zi = __builtin_amdgcn_mfma_f32_32x32x16_bf16(A, Bi, zi, 0, 0, 0); } }
;             unsigned xcb[16], pk[16];
; #pragma unroll
;             for (int v = 0; v < 16; ++v) { const int s = sbase + v; const int tl = dir == 0 ? s : 255 - s; xcb[v] = *(const LAS bf16_t*)(XC + tl * XC_PITCH + chl * 2);
;                 if (dir == 0) pk[v] = *(const LAS bf16_t*)(TIN + tl * IO_NP + nl * 2); else pk[v] = *(const LAS unsigned*)(TIN + tl * IO_WP + nl * 4); }
;             float Pp = 1.f, E = 0.f;
; #pragma unroll
;             for (int v = 0; v < 16; ++v) {
;                 const float xcv = __uint_as_float(xcb[v] << 16);
;                 const float r = __builtin_amdgcn_rcpf(1.0f + __builtin_amdgcn_exp2f(zr[v]));
;                 const float ig = __builtin_amdgcn_rcpf(1.0f + __builtin_amdgcn_exp2f(zi[v]));
;                 const float a = __builtin_amdgcn_exp2f(cl * r);
;                 const float sq = __builtin_amdgcn_sqrtf(fmaf(-a, a, 1.0f));
.LBB0_311:
	ds_read_b128 v[128:131], v172
	ds_read_b128 v[48:51], v173
	ds_read_b128 v[132:135], v172 offset:32
	ds_read_b128 v[52:55], v173 offset:32
	ds_read_b128 v[224:227], v172 offset:64
	ds_read_b128 v[56:59], v173 offset:64
	ds_read_b128 v[228:231], v172 offset:96
	ds_read_b128 v[60:63], v173 offset:96
	ds_read_b128 v[232:235], v172 offset:128
	ds_read_b128 v[236:239], v172 offset:160
	ds_read_b128 v[240:243], v172 offset:192
	ds_read_b128 v[244:247], v172 offset:224
	ds_read_b128 v[248:251], v173 offset:8704
	ds_read_b128 v[146:149], v173 offset:8736
	s_waitcnt lgkmcnt(12)
	v_mfma_f32_32x32x16_bf16 v[32:47], v[128:131], v[48:51], v[0:15]
	ds_read_b128 v[48:51], v173 offset:128
	s_waitcnt lgkmcnt(11)
	v_mfma_f32_32x32x16_bf16 v[32:47], v[132:135], v[52:55], v[32:47]
	ds_read_b128 v[52:55], v173 offset:160
	s_waitcnt lgkmcnt(10)
	v_mfma_f32_32x32x16_bf16 v[32:47], v[224:227], v[56:59], v[32:47]
	ds_read_b128 v[56:59], v173 offset:192
	s_waitcnt lgkmcnt(9)
	v_mfma_f32_32x32x16_bf16 v[32:47], v[228:231], v[60:63], v[32:47]
	ds_read_b128 v[60:63], v173 offset:224
	s_waitcnt lgkmcnt(3)
	v_mfma_f32_32x32x16_bf16 v[32:47], v[232:235], v[48:51], v[32:47]
	s_waitcnt lgkmcnt(2)
	v_mfma_f32_32x32x16_bf16 v[32:47], v[236:239], v[52:55], v[32:47]
	s_waitcnt lgkmcnt(1)
	v_mfma_f32_32x32x16_bf16 v[32:47], v[240:243], v[56:59], v[32:47]
	s_waitcnt lgkmcnt(0)
	v_mfma_f32_32x32x16_bf16 v[32:47], v[244:247], v[60:63], v[32:47]
	v_mfma_f32_32x32x16_bf16 v[48:63], v[128:131], v[248:251], v[16:31]
	ds_read_b128 v[128:131], v173 offset:8768
	s_nop 9
	v_exp_f32_e32 v32, v32
	v_exp_f32_e32 v33, v33
	v_exp_f32_e32 v34, v34
	v_exp_f32_e32 v35, v35
	v_exp_f32_e32 v36, v36
	v_exp_f32_e32 v37, v37
	v_exp_f32_e32 v38, v38
	v_exp_f32_e32 v39, v39
	v_mfma_f32_32x32x16_bf16 v[48:63], v[132:135], v[146:149], v[48:63]
	ds_read_b128 v[132:135], v173 offset:8800
	v_exp_f32_e32 v40, v40
	v_exp_f32_e32 v41, v41
	v_exp_f32_e32 v42, v42
	v_exp_f32_e32 v43, v43
	v_exp_f32_e32 v44, v44
	v_exp_f32_e32 v45, v45
	v_exp_f32_e32 v46, v46
	v_exp_f32_e32 v47, v47
	s_waitcnt lgkmcnt(1)
	v_mfma_f32_32x32x16_bf16 v[48:63], v[224:227], v[128:131], v[48:63]
	ds_read_b128 v[224:227], v173 offset:8832
	v_fma_f32 v32, v32, v159, v159
	v_fma_f32 v33, v33, v159, v159
	v_fma_f32 v34, v34, v159, v159
	v_fma_f32 v35, v35, v159, v159
	v_fma_f32 v36, v36, v159, v159
	v_fma_f32 v37, v37, v159, v159
	v_fma_f32 v38, v38, v159, v159
	v_fma_f32 v39, v39, v159, v159
	s_waitcnt lgkmcnt(1)
	v_mfma_f32_32x32x16_bf16 v[48:63], v[228:231], v[132:135], v[48:63]
	ds_read_b128 v[228:231], v173 offset:8864
	v_fma_f32 v40, v40, v159, v159
	v_fma_f32 v41, v41, v159, v159
	v_fma_f32 v42, v42, v159, v159
	v_fma_f32 v43, v43, v159, v159
	v_fma_f32 v44, v44, v159, v159
	v_fma_f32 v45, v45, v159, v159
	v_fma_f32 v46, v46, v159, v159
	v_fma_f32 v47, v47, v159, v159
	s_waitcnt lgkmcnt(1)
	v_mfma_f32_32x32x16_bf16 v[48:63], v[232:235], v[224:227], v[48:63]
	ds_read_b128 v[128:131], v173 offset:8896
	v_rcp_f32_e32 v32, v32
	v_rcp_f32_e32 v33, v33
	v_rcp_f32_e32 v34, v34
	v_rcp_f32_e32 v35, v35
	v_rcp_f32_e32 v36, v36
	v_rcp_f32_e32 v37, v37
	v_rcp_f32_e32 v38, v38
	v_rcp_f32_e32 v39, v39
	s_waitcnt lgkmcnt(1)
	v_mfma_f32_32x32x16_bf16 v[48:63], v[236:239], v[228:231], v[48:63]
	ds_read_b128 v[132:135], v173 offset:8928
	v_rcp_f32_e32 v40, v40
	v_rcp_f32_e32 v41, v41
	v_rcp_f32_e32 v42, v42
	v_rcp_f32_e32 v43, v43
	v_rcp_f32_e32 v44, v44
	v_rcp_f32_e32 v45, v45
	v_rcp_f32_e32 v46, v46
	v_rcp_f32_e32 v47, v47
	s_waitcnt lgkmcnt(1)
	v_mfma_f32_32x32x16_bf16 v[48:63], v[240:243], v[128:131], v[48:63]
	v_exp_f32_e32 v32, v32
	v_exp_f32_e32 v33, v33
	v_exp_f32_e32 v34, v34
	v_exp_f32_e32 v35, v35
	v_exp_f32_e32 v36, v36
	v_exp_f32_e32 v37, v37
	v_exp_f32_e32 v38, v38
	v_exp_f32_e32 v39, v39
	s_waitcnt lgkmcnt(0)
; #define LAS __attribute__((address_space(3)))
; template <int dir>
; __device__ __forceinline__ void lru_pass(LAS unsigned char* lds, const Params& P, int b, int h, int q, bool dry) {
;     ...
;             for (int v = 0; v < 16; ++v) { const int s = sbase + v; const int tl = dir == 0 ? s : 255 - s; xcb[v] = *(const LAS bf16_t*)(XC + tl * XC_PITCH + chl * 2);
;                 if (dir == 0) pk[v] = *(const LAS bf16_t*)(TIN + tl * IO_NP + nl * 2); else pk[v] = *(const LAS unsigned*)(TIN + tl * IO_WP + nl * 4); }
;             float Pp = 1.f, E = 0.f;
; #pragma unroll
;             for (int v = 0; v < 16; ++v) {
;                 const float xcv = __uint_as_float(xcb[v] << 16);
;                 const float r = __builtin_amdgcn_rcpf(1.0f + __builtin_amdgcn_exp2f(zr[v]));
;                 const float ig = __builtin_amdgcn_rcpf(1.0f + __builtin_amdgcn_exp2f(zi[v]));
;                 const float a = __builtin_amdgcn_exp2f(cl * r);
;                 const float sq = __builtin_amdgcn_sqrtf(fmaf(-a, a, 1.0f));
;                 const float u = sq * ig * xcv;
;                 E = fmaf(a, E, u); Pp *= a; zr[v] = E; zi[v] = Pp; }
;             const float Po = __shfl_xor(Pp, 32), Eo = __shfl_xor(E, 32);
;             const float P0 = g ? Po : Pp, E0 = g ? Eo : E, P1 = g ? Pp : Po, E1 = g ? E : Eo;
;             if (g == 0) { AGG[(wid * 2 + 0) * 32 + nl] = P0 * P1; AGG[(wid * 2 + 1) * 32 + nl] = fmaf(P1, E0, E1); }
	v_mfma_f32_32x32x16_bf16 v[48:63], v[244:247], v[132:135], v[48:63]
	v_exp_f32_e32 v40, v40
	v_exp_f32_e32 v41, v41
	v_exp_f32_e32 v42, v42
	v_exp_f32_e32 v43, v43
	v_exp_f32_e32 v44, v44
	v_exp_f32_e32 v45, v45
	v_exp_f32_e32 v46, v46
	v_exp_f32_e32 v47, v47
	ds_read_u16_d16_hi v162, v174
	ds_read_b32 v226, v175
	ds_read_u16_d16_hi v163, v176
	ds_read_b32 v225, v177
	ds_read_u16_d16_hi v232, v178
	ds_read_b32 v224, v179
	ds_read_u16_d16_hi v233, v180
	ds_read_b32 v223, v181
	ds_read_u16_d16_hi v234, v182
	ds_read_b32 v135, v183
	ds_read_u16_d16_hi v235, v184
	ds_read_b32 v134, v185
	ds_read_u16_d16_hi v236, v186
	ds_read_b32 v133, v187
	ds_read_u16_d16_hi v237, v188
	ds_read_b32 v131, v189
	ds_read_u16_d16_hi v146, v190
	ds_read_b32 v132, v191
	ds_read_u16_d16_hi v147, v192
	ds_read_b32 v130, v193
	ds_read_u16_d16_hi v148, v194
	ds_read_b32 v129, v195
	ds_read_u16_d16_hi v149, v196
	ds_read_b32 v128, v197
	ds_read_u16_d16_hi v239, v198
	ds_read_b32 v67, v199
	ds_read_u16_d16_hi v240, v200
	ds_read_b32 v66, v201
	ds_read_u16_d16_hi v241, v202
	ds_read_b32 v64, v203
	ds_read_u16_d16_hi v242, v204
	ds_read_b32 v251, v205
	v_exp_f32_e32 v48, v48
	v_exp_f32_e32 v49, v49
	v_exp_f32_e32 v50, v50
	v_exp_f32_e32 v51, v51
	v_exp_f32_e32 v52, v52
	v_exp_f32_e32 v53, v53
	v_exp_f32_e32 v54, v54
	v_exp_f32_e32 v55, v55
	v_exp_f32_e32 v56, v56
	v_exp_f32_e32 v57, v57
	v_exp_f32_e32 v58, v58
	v_exp_f32_e32 v59, v59
	v_exp_f32_e32 v60, v60
	v_exp_f32_e32 v61, v61
	v_exp_f32_e32 v62, v62
	v_exp_f32_e32 v63, v63
	v_pk_add_f32 v[48:49], v[48:49], 1.0 op_sel_hi:[1,0]
	v_pk_add_f32 v[50:51], v[50:51], 1.0 op_sel_hi:[1,0]
	v_pk_add_f32 v[52:53], v[52:53], 1.0 op_sel_hi:[1,0]
	v_pk_add_f32 v[54:55], v[54:55], 1.0 op_sel_hi:[1,0]
	v_pk_add_f32 v[56:57], v[56:57], 1.0 op_sel_hi:[1,0]
	v_pk_add_f32 v[58:59], v[58:59], 1.0 op_sel_hi:[1,0]
	v_pk_add_f32 v[60:61], v[60:61], 1.0 op_sel_hi:[1,0]
	v_pk_add_f32 v[62:63], v[62:63], 1.0 op_sel_hi:[1,0]
	v_rcp_f32_e32 v48, v48
	v_rcp_f32_e32 v49, v49
	v_rcp_f32_e32 v50, v50
	v_rcp_f32_e32 v51, v51
	v_rcp_f32_e32 v52, v52
	v_rcp_f32_e32 v53, v53
	v_rcp_f32_e32 v54, v54
	v_rcp_f32_e32 v55, v55
	v_rcp_f32_e32 v56, v56
	v_rcp_f32_e32 v57, v57
	v_rcp_f32_e32 v58, v58
	v_rcp_f32_e32 v59, v59
	v_rcp_f32_e32 v60, v60
	v_rcp_f32_e32 v61, v61
	v_rcp_f32_e32 v62, v62
	v_rcp_f32_e32 v63, v63
	s_waitcnt lgkmcnt(0)
	v_pk_fma_f32 v[244:245], v[32:33], v[32:33], 1.0 op_sel_hi:[1,1,0] neg_lo:[1,0,0] neg_hi:[1,0,0]
	v_pk_fma_f32 v[246:247], v[34:35], v[34:35], 1.0 op_sel_hi:[1,1,0] neg_lo:[1,0,0] neg_hi:[1,0,0]
	v_sqrt_f32_e32 v244, v244
	v_sqrt_f32_e32 v245, v245
	v_sqrt_f32_e32 v246, v246
	v_sqrt_f32_e32 v247, v247
	v_pk_mul_f32 v[244:245], v[244:245], v[48:49]
	v_pk_mul_f32 v[246:247], v[246:247], v[50:51]
	v_mul_f32_e32 v49, v244, v162
	v_mul_f32_e32 v228, v245, v163
	v_mul_f32_e32 v229, v246, v232
	v_mul_f32_e32 v230, v247, v233
	v_pk_fma_f32 v[244:245], v[36:37], v[36:37], 1.0 op_sel_hi:[1,1,0] neg_lo:[1,0,0] neg_hi:[1,0,0]
	v_pk_fma_f32 v[246:247], v[38:39], v[38:39], 1.0 op_sel_hi:[1,1,0] neg_lo:[1,0,0] neg_hi:[1,0,0]
	v_sqrt_f32_e32 v244, v244
	v_sqrt_f32_e32 v245, v245
	v_sqrt_f32_e32 v246, v246
	v_sqrt_f32_e32 v247, v247
	v_pk_mul_f32 v[244:245], v[244:245], v[52:53]
	v_pk_mul_f32 v[246:247], v[246:247], v[54:55]
	v_mul_f32_e32 v231, v244, v234
	v_mul_f32_e32 v232, v245, v235
	v_mul_f32_e32 v233, v246, v236
	v_mul_f32_e32 v234, v247, v237
	v_pk_fma_f32 v[244:245], v[40:41], v[40:41], 1.0 op_sel_hi:[1,1,0] neg_lo:[1,0,0] neg_hi:[1,0,0]
	v_pk_fma_f32 v[246:247], v[42:43], v[42:43], 1.0 op_sel_hi:[1,1,0] neg_lo:[1,0,0] neg_hi:[1,0,0]
	v_sqrt_f32_e32 v244, v244
	v_sqrt_f32_e32 v245, v245
	v_sqrt_f32_e32 v246, v246
	v_sqrt_f32_e32 v247, v247
	v_pk_mul_f32 v[244:245], v[244:245], v[56:57]
	v_pk_mul_f32 v[246:247], v[246:247], v[58:59]
	v_mul_f32_e32 v235, v244, v146
	v_mul_f32_e32 v236, v245, v147
	v_mul_f32_e32 v237, v246, v148
	v_mul_f32_e32 v238, v247, v149
	v_pk_fma_f32 v[244:245], v[44:45], v[44:45], 1.0 op_sel_hi:[1,1,0] neg_lo:[1,0,0] neg_hi:[1,0,0]
	v_pk_fma_f32 v[246:247], v[46:47], v[46:47], 1.0 op_sel_hi:[1,1,0] neg_lo:[1,0,0] neg_hi:[1,0,0]
	v_sqrt_f32_e32 v244, v244
	v_sqrt_f32_e32 v245, v245
	v_sqrt_f32_e32 v246, v246
	v_sqrt_f32_e32 v247, v247
	v_pk_mul_f32 v[244:245], v[244:245], v[60:61]
	v_pk_mul_f32 v[246:247], v[246:247], v[62:63]
	v_mul_f32_e32 v239, v244, v239
	v_mul_f32_e32 v240, v245, v240
	v_mul_f32_e32 v63, v246, v241
	v_mul_f32_e32 v241, v247, v242
	v_mov_b32_e32 v227, v32
	v_fmac_f32_e32 v49, 0, v32
	v_fmac_f32_e32 v228, v33, v49
	v_mul_f32_e32 v50, v227, v33
	v_fmac_f32_e32 v229, v34, v228
	v_mul_f32_e32 v51, v50, v34
	v_fmac_f32_e32 v230, v35, v229
	v_mul_f32_e32 v52, v51, v35
	v_fmac_f32_e32 v231, v36, v230
	v_mul_f32_e32 v53, v52, v36
	v_fmac_f32_e32 v232, v37, v231
	v_mul_f32_e32 v54, v53, v37
	v_fmac_f32_e32 v233, v38, v232
	v_mul_f32_e32 v55, v54, v38
	v_fmac_f32_e32 v234, v39, v233
	v_mul_f32_e32 v56, v55, v39
	v_fmac_f32_e32 v235, v40, v234
	v_mul_f32_e32 v57, v56, v40
	v_fmac_f32_e32 v236, v41, v235
	v_mul_f32_e32 v58, v57, v41
	v_fmac_f32_e32 v237, v42, v236
	v_mul_f32_e32 v59, v58, v42
	v_fmac_f32_e32 v238, v43, v237
	v_mul_f32_e32 v60, v59, v43
	v_fmac_f32_e32 v239, v44, v238
	v_mul_f32_e32 v61, v60, v44
	v_fmac_f32_e32 v240, v45, v239
	v_mul_f32_e32 v62, v61, v45
	v_fmac_f32_e32 v63, v46, v240
	v_mul_f32_e32 v243, v62, v46
	v_fmac_f32_e32 v241, v47, v63
	v_mul_f32_e32 v242, v243, v47
	v_mov_b32_e32 v244, v242
	v_mov_b32_e32 v246, v242
	v_mov_b32_e32 v245, v241
	v_mov_b32_e32 v247, v241
	s_nop 1
	v_permlane32_swap_b32 v244, v246
	v_permlane32_swap_b32 v245, v247
	s_and_saveexec_b64 s[18:19], vcc
	s_cbranch_execz .LBB0_313
	v_fma_f32 v32, v246, v245, v247
	v_mul_f32_e32 v33, v244, v246
	v_add_u32_e32 v35, s98, v254
	ds_write2_b32 v35, v33, v32 offset1:32
